# plus P2: waves skip matrix sections whose PV and QK tiles are fully chunk-masked for their rows
# baseline (speedup 1.0000x reference)
.LBB0_678:
	s_waitcnt lgkmcnt(0)
	s_barrier
	s_setprio 1
	s_sub_i32 s100, s82, 64
	s_cmp_gt_i32 s100, s84
	s_cbranch_scc1 .Lmsk_0
	ds_read_b64_tr_b16 v[64:65], v175 offset:0x4000
	ds_read_b64_tr_b16 v[66:67], v175 offset:0x4800
	ds_read_b64_tr_b16 v[68:69], v175 offset:0x5000
	ds_read_b64_tr_b16 v[70:71], v175 offset:0x5800
	ds_read_b64_tr_b16 v[72:73], v175 offset:0x6000
	ds_read_b64_tr_b16 v[74:75], v175 offset:0x6800
	ds_read_b64_tr_b16 v[76:77], v175 offset:0x7000
	ds_read_b64_tr_b16 v[78:79], v175 offset:0x7800
	ds_read_b64_tr_b16 v[80:81], v175 offset:0x4200
	ds_read_b64_tr_b16 v[82:83], v175 offset:0x4a00
	ds_read_b64_tr_b16 v[84:85], v175 offset:0x5200
	ds_read_b64_tr_b16 v[86:87], v175 offset:0x5a00
	ds_read_b64_tr_b16 v[88:89], v175 offset:0x6200
	ds_read_b64_tr_b16 v[90:91], v175 offset:0x6a00
	ds_read_b64_tr_b16 v[92:93], v175 offset:0x7200
	ds_read_b64_tr_b16 v[94:95], v175 offset:0x7a00
	s_waitcnt lgkmcnt(14)
	s_nop 0
	v_mfma_f32_32x32x16_bf16 v[48:63], v[156:159], v[64:67], v[48:63]
	ds_read_b64_tr_b16 v[64:65], v175 offset:0x4400
	ds_read_b64_tr_b16 v[66:67], v175 offset:0x4c00
	s_waitcnt lgkmcnt(14)
	v_mfma_f32_32x32x16_bf16 v[48:63], v[152:155], v[68:71], v[48:63]
	ds_read_b64_tr_b16 v[68:69], v175 offset:0x5400
	ds_read_b64_tr_b16 v[70:71], v175 offset:0x5c00
	s_waitcnt lgkmcnt(14)
	v_mfma_f32_32x32x16_bf16 v[48:63], v[148:151], v[72:75], v[48:63]
	ds_read_b64_tr_b16 v[72:73], v175 offset:0x6400
	ds_read_b64_tr_b16 v[74:75], v175 offset:0x6c00
	s_waitcnt lgkmcnt(14)
	v_mfma_f32_32x32x16_bf16 v[48:63], v[144:147], v[76:79], v[48:63]
	ds_read_b64_tr_b16 v[76:77], v175 offset:0x7400
	ds_read_b64_tr_b16 v[78:79], v175 offset:0x7c00
	s_waitcnt lgkmcnt(14)
	v_mfma_f32_32x32x16_bf16 v[32:47], v[156:159], v[80:83], v[32:47]
	ds_read_b64_tr_b16 v[80:81], v175 offset:0x4600
	ds_read_b64_tr_b16 v[82:83], v175 offset:0x4e00
	s_waitcnt lgkmcnt(14)
	v_mfma_f32_32x32x16_bf16 v[32:47], v[152:155], v[84:87], v[32:47]
	ds_read_b64_tr_b16 v[84:85], v175 offset:0x5600
	ds_read_b64_tr_b16 v[86:87], v175 offset:0x5e00
	s_waitcnt lgkmcnt(14)
	v_mfma_f32_32x32x16_bf16 v[32:47], v[148:151], v[88:91], v[32:47]
	ds_read_b64_tr_b16 v[88:89], v175 offset:0x6600
	ds_read_b64_tr_b16 v[90:91], v175 offset:0x6e00
	s_waitcnt lgkmcnt(14)
	v_mfma_f32_32x32x16_bf16 v[32:47], v[144:147], v[92:95], v[32:47]
	ds_read_b64_tr_b16 v[92:93], v175 offset:0x7600
	ds_read_b64_tr_b16 v[94:95], v175 offset:0x7e00
	s_waitcnt lgkmcnt(14)
	v_mfma_f32_32x32x16_bf16 v[16:31], v[156:159], v[64:67], v[16:31]
	ds_read_b128 v[64:67], v182 offset:0x8000
	s_waitcnt lgkmcnt(13)
	v_mfma_f32_32x32x16_bf16 v[16:31], v[152:155], v[68:71], v[16:31]
	ds_read_b128 v[68:71], v182 offset:0xa000
	s_waitcnt lgkmcnt(12)
	v_mfma_f32_32x32x16_bf16 v[16:31], v[148:151], v[72:75], v[16:31]
	ds_read_b128 v[188:191], v181 offset:0x8000
	s_waitcnt lgkmcnt(11)
	v_mfma_f32_32x32x16_bf16 v[16:31], v[144:147], v[76:79], v[16:31]
	ds_read_b128 v[192:195], v181 offset:0xa000
	s_waitcnt lgkmcnt(10)
	v_mfma_f32_32x32x16_bf16 v[0:15], v[156:159], v[80:83], v[0:15]
	ds_read_b128 v[156:159], v180 offset:0x8000
	s_waitcnt lgkmcnt(9)
	v_mfma_f32_32x32x16_bf16 v[0:15], v[152:155], v[84:87], v[0:15]
	ds_read_b128 v[152:155], v180 offset:0xa000
	s_waitcnt lgkmcnt(8)
	v_mfma_f32_32x32x16_bf16 v[0:15], v[148:151], v[88:91], v[0:15]
	ds_read_b128 v[148:151], v177 offset:0x8000
	s_waitcnt lgkmcnt(7)
	v_mfma_f32_32x32x16_bf16 v[0:15], v[144:147], v[92:95], v[0:15]
	ds_read_b128 v[144:147], v177 offset:0xa000
	s_waitcnt lgkmcnt(7)
	v_mfma_f32_32x32x16_bf16 v[80:95], v[64:67], v[140:143], 0
	ds_read_b128 v[196:199], v165 offset:0x8000
	s_waitcnt lgkmcnt(7)
	v_mfma_f32_32x32x16_bf16 v[64:79], v[68:71], v[140:143], 0
	ds_read_b128 v[200:203], v165 offset:0xa000
	s_waitcnt lgkmcnt(7)
	v_mfma_f32_32x32x16_bf16 v[80:95], v[188:191], v[136:139], v[80:95]
	ds_read_b128 v[188:191], v176 offset:0x8000
	s_waitcnt lgkmcnt(7)
	v_mfma_f32_32x32x16_bf16 v[64:79], v[192:195], v[136:139], v[64:79]
	ds_read_b128 v[192:195], v176 offset:0xa000
	s_waitcnt lgkmcnt(7)
	v_mfma_f32_32x32x16_bf16 v[80:95], v[156:159], v[132:135], v[80:95]
	ds_read_b128 v[156:159], v178 offset:0x8000
	s_waitcnt lgkmcnt(7)
	v_mfma_f32_32x32x16_bf16 v[64:79], v[152:155], v[132:135], v[64:79]
	ds_read_b128 v[152:155], v178 offset:0xa000
	s_waitcnt lgkmcnt(7)
	v_mfma_f32_32x32x16_bf16 v[80:95], v[148:151], v[128:131], v[80:95]
	ds_read_b128 v[148:151], v179 offset:0x8000
	s_waitcnt lgkmcnt(7)
	v_mfma_f32_32x32x16_bf16 v[64:79], v[144:147], v[128:131], v[64:79]
	ds_read_b128 v[144:147], v179 offset:0xa000
	s_waitcnt lgkmcnt(7)
	v_mfma_f32_32x32x16_bf16 v[80:95], v[196:199], v[124:127], v[80:95]
	s_waitcnt lgkmcnt(6)
	v_mfma_f32_32x32x16_bf16 v[64:79], v[200:203], v[124:127], v[64:79]
	s_waitcnt lgkmcnt(5)
	v_mfma_f32_32x32x16_bf16 v[80:95], v[188:191], v[120:123], v[80:95]
	s_waitcnt lgkmcnt(4)
	v_mfma_f32_32x32x16_bf16 v[64:79], v[192:195], v[120:123], v[64:79]
	s_waitcnt lgkmcnt(3)
	v_mfma_f32_32x32x16_bf16 v[80:95], v[156:159], v[116:119], v[80:95]
	s_waitcnt lgkmcnt(2)
	v_mfma_f32_32x32x16_bf16 v[64:79], v[152:155], v[116:119], v[64:79]
	s_waitcnt lgkmcnt(1)
	v_mfma_f32_32x32x16_bf16 v[80:95], v[148:151], v[112:115], v[80:95]
	s_waitcnt lgkmcnt(0)
	v_mfma_f32_32x32x16_bf16 v[64:79], v[144:147], v[112:115], v[64:79]
.Lmsk_0:
	s_setprio 0
	s_waitcnt lgkmcnt(0)
	s_barrier
	s_cmp_le_i32 s82, s84
	s_mov_b64 s[2:3], -1
	s_cbranch_scc0 .LBB0_682
	s_add_i32 s2, s82, 63
	s_cmp_le_i32 s2, s84
	s_cbranch_scc1 .LBB0_681
	v_cmp_gt_i32_e64 s[60:61], 26, v186
	v_cmp_gt_i32_e64 s[62:63], 27, v186
	v_cmp_gt_i32_e64 s[58:59], 25, v186
	s_and_b64 s[60:61], s[62:63], s[60:61]
	v_cmp_gt_i32_e64 s[56:57], 24, v186
	s_and_b64 s[58:59], s[60:61], s[58:59]
	v_cmp_gt_i32_e64 s[54:55], 19, v186
	s_and_b64 s[56:57], s[58:59], s[56:57]
	v_cmp_gt_i32_e64 s[52:53], 18, v186
	s_and_b64 s[54:55], s[56:57], s[54:55]
	v_cmp_gt_i32_e64 s[50:51], 17, v186
	s_and_b64 s[52:53], s[54:55], s[52:53]
	v_cmp_gt_i32_e64 s[48:49], 16, v186
	s_and_b64 s[50:51], s[52:53], s[50:51]
	v_cmp_gt_i32_e64 s[46:47], 11, v186
	s_and_b64 s[48:49], s[50:51], s[48:49]
	v_cmp_gt_i32_e64 s[44:45], 10, v186
	s_and_b64 s[46:47], s[48:49], s[46:47]
	v_cmp_gt_i32_e64 s[42:43], 9, v186
	s_and_b64 s[44:45], s[46:47], s[44:45]
	v_cmp_gt_i32_e64 s[40:41], 8, v186
	s_and_b64 s[42:43], s[44:45], s[42:43]
	v_cmp_gt_i32_e64 s[38:39], 3, v186
	s_and_b64 s[40:41], s[42:43], s[40:41]
	v_cmp_gt_i32_e64 s[36:37], 2, v186
	s_and_b64 s[38:39], s[40:41], s[38:39]
	v_cmp_gt_i32_e64 s[34:35], 1, v186
	s_and_b64 s[36:37], s[38:39], s[36:37]
	v_cmp_gt_i32_e64 s[30:31], 0, v186
	s_and_b64 s[34:35], s[36:37], s[34:35]
	s_and_b64 s[30:31], s[34:35], s[30:31]
	v_cmp_gt_i32_e64 s[28:29], 58, v186
	v_cndmask_b32_e64 v80, v80, v231, s[30:31]
	v_cmp_gt_i32_e64 s[30:31], 59, v186
	v_cmp_gt_i32_e64 s[26:27], 57, v186
	s_and_b64 s[28:29], s[30:31], s[28:29]
	v_cmp_gt_i32_e64 s[24:25], 56, v186
	s_and_b64 s[26:27], s[28:29], s[26:27]
	v_cmp_gt_i32_e64 s[22:23], 51, v186
	s_and_b64 s[24:25], s[26:27], s[24:25]
	v_cmp_gt_i32_e64 s[20:21], 50, v186
	s_and_b64 s[22:23], s[24:25], s[22:23]
	v_cmp_gt_i32_e64 s[18:19], 49, v186
	s_and_b64 s[20:21], s[22:23], s[20:21]
	v_cmp_gt_i32_e64 s[16:17], 48, v186
	s_and_b64 s[18:19], s[20:21], s[18:19]
	v_cmp_gt_i32_e64 s[14:15], 43, v186
	s_and_b64 s[16:17], s[18:19], s[16:17]
	v_cmp_gt_i32_e64 s[12:13], 42, v186
	s_and_b64 s[14:15], s[16:17], s[14:15]
	v_cmp_gt_i32_e64 s[10:11], 41, v186
	s_and_b64 s[12:13], s[14:15], s[12:13]
	v_cmp_gt_i32_e64 s[8:9], 40, v186
	s_and_b64 s[10:11], s[12:13], s[10:11]
	v_cmp_gt_i32_e64 s[6:7], 35, v186
	s_and_b64 s[8:9], s[10:11], s[8:9]
	v_cmp_gt_i32_e64 s[4:5], 34, v186
	s_and_b64 s[6:7], s[8:9], s[6:7]
	v_cmp_gt_i32_e64 s[2:3], 33, v186
	s_and_b64 s[4:5], s[6:7], s[4:5]
	v_cmp_gt_i32_e32 vcc, 32, v186
	s_and_b64 s[2:3], s[4:5], s[2:3]
	s_and_b64 vcc, s[2:3], vcc
	v_cndmask_b32_e64 v95, v95, v231, s[62:63]
	v_cndmask_b32_e64 v94, v94, v231, s[60:61]
	v_cndmask_b32_e64 v93, v93, v231, s[58:59]
	v_cndmask_b32_e64 v92, v92, v231, s[56:57]
	v_cndmask_b32_e64 v91, v91, v231, s[54:55]
	v_cndmask_b32_e64 v90, v90, v231, s[52:53]
	v_cndmask_b32_e64 v89, v89, v231, s[50:51]
	v_cndmask_b32_e64 v88, v88, v231, s[48:49]
	v_cndmask_b32_e64 v87, v87, v231, s[46:47]
	v_cndmask_b32_e64 v86, v86, v231, s[44:45]
	v_cndmask_b32_e64 v85, v85, v231, s[42:43]
	v_cndmask_b32_e64 v84, v84, v231, s[40:41]
	v_cndmask_b32_e64 v83, v83, v231, s[38:39]
	v_cndmask_b32_e64 v82, v82, v231, s[36:37]
	v_cndmask_b32_e64 v81, v81, v231, s[34:35]
	v_cndmask_b32_e64 v79, v79, v231, s[30:31]
	v_cndmask_b32_e64 v78, v78, v231, s[28:29]
	v_cndmask_b32_e64 v77, v77, v231, s[26:27]
	v_cndmask_b32_e64 v76, v76, v231, s[24:25]
	v_cndmask_b32_e64 v75, v75, v231, s[22:23]
	v_cndmask_b32_e64 v74, v74, v231, s[20:21]
	v_cndmask_b32_e64 v73, v73, v231, s[18:19]
	v_cndmask_b32_e64 v72, v72, v231, s[16:17]
	v_cndmask_b32_e64 v71, v71, v231, s[14:15]
	v_cndmask_b32_e64 v70, v70, v231, s[12:13]
	v_cndmask_b32_e64 v69, v69, v231, s[10:11]
	v_cndmask_b32_e64 v68, v68, v231, s[8:9]
	v_cndmask_b32_e64 v67, v67, v231, s[6:7]
	v_cndmask_b32_e64 v66, v66, v231, s[4:5]
	v_cndmask_b32_e64 v65, v65, v231, s[2:3]
	v_cndmask_b32_e32 v64, v64, v231, vcc

.LBB0_690:
	s_setprio 1
	s_sub_i32 s99, s82, 64
	s_sub_i32 s100, s82, 0x80
	s_cmp_gt_i32 s100, s84
	s_cbranch_scc1 .Lmsk_1
	ds_read_b64_tr_b16 v[64:65], v175 offset:0
	ds_read_b64_tr_b16 v[66:67], v175 offset:0x800
	ds_read_b64_tr_b16 v[68:69], v175 offset:0x1000
	ds_read_b64_tr_b16 v[70:71], v175 offset:0x1800
	ds_read_b64_tr_b16 v[72:73], v175 offset:0x2000
	ds_read_b64_tr_b16 v[74:75], v175 offset:0x2800
	ds_read_b64_tr_b16 v[76:77], v175 offset:0x3000
	ds_read_b64_tr_b16 v[78:79], v175 offset:0x3800
	ds_read_b64_tr_b16 v[80:81], v175 offset:0x200
	ds_read_b64_tr_b16 v[82:83], v175 offset:0xa00
	ds_read_b64_tr_b16 v[84:85], v175 offset:0x1200
	ds_read_b64_tr_b16 v[86:87], v175 offset:0x1a00
	ds_read_b64_tr_b16 v[88:89], v175 offset:0x2200
	ds_read_b64_tr_b16 v[90:91], v175 offset:0x2a00
	ds_read_b64_tr_b16 v[92:93], v175 offset:0x3200
	ds_read_b64_tr_b16 v[94:95], v175 offset:0x3a00
	s_waitcnt lgkmcnt(14)
	s_nop 0
	v_mfma_f32_32x32x16_bf16 v[48:63], v[156:159], v[64:67], v[48:63]
	ds_read_b64_tr_b16 v[64:65], v175 offset:0x400
	ds_read_b64_tr_b16 v[66:67], v175 offset:0xc00
	s_waitcnt lgkmcnt(14)
	v_mfma_f32_32x32x16_bf16 v[48:63], v[152:155], v[68:71], v[48:63]
	ds_read_b64_tr_b16 v[68:69], v175 offset:0x1400
	ds_read_b64_tr_b16 v[70:71], v175 offset:0x1c00
	s_waitcnt lgkmcnt(14)
	v_mfma_f32_32x32x16_bf16 v[48:63], v[148:151], v[72:75], v[48:63]
	ds_read_b64_tr_b16 v[72:73], v175 offset:0x2400
	ds_read_b64_tr_b16 v[74:75], v175 offset:0x2c00
	s_waitcnt lgkmcnt(14)
	v_mfma_f32_32x32x16_bf16 v[48:63], v[144:147], v[76:79], v[48:63]
	ds_read_b64_tr_b16 v[76:77], v175 offset:0x3400
	ds_read_b64_tr_b16 v[78:79], v175 offset:0x3c00
	s_waitcnt lgkmcnt(14)
	v_mfma_f32_32x32x16_bf16 v[32:47], v[156:159], v[80:83], v[32:47]
	ds_read_b64_tr_b16 v[80:81], v175 offset:0x600
	ds_read_b64_tr_b16 v[82:83], v175 offset:0xe00
	s_waitcnt lgkmcnt(14)
	v_mfma_f32_32x32x16_bf16 v[32:47], v[152:155], v[84:87], v[32:47]
	ds_read_b64_tr_b16 v[84:85], v175 offset:0x1600
	ds_read_b64_tr_b16 v[86:87], v175 offset:0x1e00
	s_waitcnt lgkmcnt(14)
	v_mfma_f32_32x32x16_bf16 v[32:47], v[148:151], v[88:91], v[32:47]
	ds_read_b64_tr_b16 v[88:89], v175 offset:0x2600
	ds_read_b64_tr_b16 v[90:91], v175 offset:0x2e00
	s_waitcnt lgkmcnt(14)
	v_mfma_f32_32x32x16_bf16 v[32:47], v[144:147], v[92:95], v[32:47]
	ds_read_b64_tr_b16 v[92:93], v175 offset:0x3600
	ds_read_b64_tr_b16 v[94:95], v175 offset:0x3e00
	s_waitcnt lgkmcnt(14)
	v_mfma_f32_32x32x16_bf16 v[16:31], v[156:159], v[64:67], v[16:31]
	ds_read_b128 v[64:67], v182 offset:0xc000
	s_waitcnt lgkmcnt(13)
	v_mfma_f32_32x32x16_bf16 v[16:31], v[152:155], v[68:71], v[16:31]
	ds_read_b128 v[68:71], v182 offset:0xe000
	s_waitcnt lgkmcnt(12)
	v_mfma_f32_32x32x16_bf16 v[16:31], v[148:151], v[72:75], v[16:31]
	ds_read_b128 v[186:189], v181 offset:0xc000
	s_waitcnt lgkmcnt(11)
	v_mfma_f32_32x32x16_bf16 v[16:31], v[144:147], v[76:79], v[16:31]
	ds_read_b128 v[190:193], v181 offset:0xe000
	s_waitcnt lgkmcnt(10)
	v_mfma_f32_32x32x16_bf16 v[0:15], v[156:159], v[80:83], v[0:15]
	ds_read_b128 v[156:159], v180 offset:0xc000
	s_waitcnt lgkmcnt(9)
	v_mfma_f32_32x32x16_bf16 v[0:15], v[152:155], v[84:87], v[0:15]
	ds_read_b128 v[152:155], v180 offset:0xe000
	s_waitcnt lgkmcnt(8)
	v_mfma_f32_32x32x16_bf16 v[0:15], v[148:151], v[88:91], v[0:15]
	ds_read_b128 v[148:151], v177 offset:0xc000
	s_waitcnt lgkmcnt(7)
	v_mfma_f32_32x32x16_bf16 v[0:15], v[144:147], v[92:95], v[0:15]
	ds_read_b128 v[144:147], v177 offset:0xe000
	s_waitcnt lgkmcnt(7)
	v_mfma_f32_32x32x16_bf16 v[80:95], v[64:67], v[140:143], 0
	ds_read_b128 v[180:183], v165 offset:0xc000
	s_waitcnt lgkmcnt(7)
	v_mfma_f32_32x32x16_bf16 v[64:79], v[68:71], v[140:143], 0
	ds_read_b128 v[140:143], v165 offset:0xe000
	s_waitcnt lgkmcnt(7)
	v_mfma_f32_32x32x16_bf16 v[80:95], v[186:189], v[136:139], v[80:95]
	ds_read_b128 v[186:189], v176 offset:0xc000
	s_waitcnt lgkmcnt(7)
	v_mfma_f32_32x32x16_bf16 v[64:79], v[190:193], v[136:139], v[64:79]
	ds_read_b128 v[136:139], v176 offset:0xe000
	s_waitcnt lgkmcnt(7)
	v_mfma_f32_32x32x16_bf16 v[80:95], v[156:159], v[132:135], v[80:95]
	ds_read_b128 v[156:159], v178 offset:0xc000
	s_waitcnt lgkmcnt(7)
	v_mfma_f32_32x32x16_bf16 v[64:79], v[152:155], v[132:135], v[64:79]
	ds_read_b128 v[132:135], v178 offset:0xe000
	s_waitcnt lgkmcnt(7)
	v_mfma_f32_32x32x16_bf16 v[80:95], v[148:151], v[128:131], v[80:95]
	ds_read_b128 v[148:151], v179 offset:0xc000
	s_waitcnt lgkmcnt(7)
	v_mfma_f32_32x32x16_bf16 v[64:79], v[144:147], v[128:131], v[64:79]
	ds_read_b128 v[128:131], v179 offset:0xe000
	s_waitcnt lgkmcnt(7)
	v_mfma_f32_32x32x16_bf16 v[80:95], v[180:183], v[124:127], v[80:95]
	s_waitcnt lgkmcnt(6)
	v_mfma_f32_32x32x16_bf16 v[64:79], v[140:143], v[124:127], v[64:79]
	s_waitcnt lgkmcnt(5)
	v_mfma_f32_32x32x16_bf16 v[80:95], v[186:189], v[120:123], v[80:95]
	s_waitcnt lgkmcnt(4)
	v_mfma_f32_32x32x16_bf16 v[64:79], v[136:139], v[120:123], v[64:79]
	s_waitcnt lgkmcnt(3)
	v_mfma_f32_32x32x16_bf16 v[80:95], v[156:159], v[116:119], v[80:95]
	s_waitcnt lgkmcnt(2)
	v_mfma_f32_32x32x16_bf16 v[64:79], v[132:135], v[116:119], v[64:79]
	s_waitcnt lgkmcnt(1)
	v_mfma_f32_32x32x16_bf16 v[80:95], v[148:151], v[112:115], v[80:95]
	s_waitcnt lgkmcnt(0)
	v_mfma_f32_32x32x16_bf16 v[64:79], v[128:131], v[112:115], v[64:79]
.Lmsk_1:
	s_setprio 0
	s_waitcnt lgkmcnt(0)
	s_barrier
	s_and_b32 s4, s78, 0xffffffc0
	s_add_i32 s1, s4, 0xc0
	s_cmp_le_i32 s1, s84
	s_mov_b64 s[2:3], -1
	s_cbranch_scc0 .LBB0_694
	s_addk_i32 s4, 0xff
	s_cmp_le_i32 s4, s84
	s_cbranch_scc1 .LBB0_693
	v_subrev_u32_e32 v112, s1, v184
	v_cmp_gt_i32_e64 s[60:61], 26, v112
	v_cmp_gt_i32_e64 s[62:63], 27, v112
	v_cmp_gt_i32_e64 s[58:59], 25, v112
	s_and_b64 s[60:61], s[62:63], s[60:61]
	v_cmp_gt_i32_e64 s[56:57], 24, v112
	s_and_b64 s[58:59], s[60:61], s[58:59]
	v_cmp_gt_i32_e64 s[54:55], 19, v112
	s_and_b64 s[56:57], s[58:59], s[56:57]
	v_cmp_gt_i32_e64 s[52:53], 18, v112
	s_and_b64 s[54:55], s[56:57], s[54:55]
	v_cmp_gt_i32_e64 s[50:51], 17, v112
	s_and_b64 s[52:53], s[54:55], s[52:53]
	v_cmp_gt_i32_e64 s[48:49], 16, v112
	s_and_b64 s[50:51], s[52:53], s[50:51]
	v_cmp_gt_i32_e64 s[46:47], 11, v112
	s_and_b64 s[48:49], s[50:51], s[48:49]
	v_cmp_gt_i32_e64 s[44:45], 10, v112
	s_and_b64 s[46:47], s[48:49], s[46:47]
	v_cmp_gt_i32_e64 s[42:43], 9, v112
	s_and_b64 s[44:45], s[46:47], s[44:45]
	v_cmp_gt_i32_e64 s[40:41], 8, v112
	s_and_b64 s[42:43], s[44:45], s[42:43]
	v_cmp_gt_i32_e64 s[38:39], 3, v112
	s_and_b64 s[40:41], s[42:43], s[40:41]
	v_cmp_gt_i32_e64 s[36:37], 2, v112
	s_and_b64 s[38:39], s[40:41], s[38:39]
	v_cmp_gt_i32_e64 s[34:35], 1, v112
	s_and_b64 s[36:37], s[38:39], s[36:37]
	v_cmp_gt_i32_e64 s[30:31], 0, v112
	s_and_b64 s[34:35], s[36:37], s[34:35]
	s_and_b64 s[30:31], s[34:35], s[30:31]
	v_cmp_gt_i32_e64 s[28:29], 58, v112
	v_cndmask_b32_e64 v80, v80, v231, s[30:31]
	v_cmp_gt_i32_e64 s[30:31], 59, v112
	v_cmp_gt_i32_e64 s[26:27], 57, v112
	s_and_b64 s[28:29], s[30:31], s[28:29]
	v_cmp_gt_i32_e64 s[24:25], 56, v112
	s_and_b64 s[26:27], s[28:29], s[26:27]
	v_cmp_gt_i32_e64 s[22:23], 51, v112
	s_and_b64 s[24:25], s[26:27], s[24:25]
	v_cmp_gt_i32_e64 s[20:21], 50, v112
	s_and_b64 s[22:23], s[24:25], s[22:23]
	v_cmp_gt_i32_e64 s[18:19], 49, v112
	s_and_b64 s[20:21], s[22:23], s[20:21]
	v_cmp_gt_i32_e64 s[16:17], 48, v112
	s_and_b64 s[18:19], s[20:21], s[18:19]
	v_cmp_gt_i32_e64 s[14:15], 43, v112
	s_and_b64 s[16:17], s[18:19], s[16:17]
	v_cmp_gt_i32_e64 s[12:13], 42, v112
	s_and_b64 s[14:15], s[16:17], s[14:15]
	v_cmp_gt_i32_e64 s[10:11], 41, v112
	s_and_b64 s[12:13], s[14:15], s[12:13]
	v_cmp_gt_i32_e64 s[8:9], 40, v112
	s_and_b64 s[10:11], s[12:13], s[10:11]
	v_cmp_gt_i32_e64 s[6:7], 35, v112
	s_and_b64 s[8:9], s[10:11], s[8:9]
	v_cmp_gt_i32_e64 s[4:5], 34, v112
	s_and_b64 s[6:7], s[8:9], s[6:7]
	v_cmp_gt_i32_e64 s[2:3], 33, v112
	s_and_b64 s[4:5], s[6:7], s[4:5]
	v_cmp_gt_i32_e32 vcc, 32, v112
	s_and_b64 s[2:3], s[4:5], s[2:3]
	s_and_b64 vcc, s[2:3], vcc
	v_cndmask_b32_e64 v95, v95, v231, s[62:63]
	v_cndmask_b32_e64 v94, v94, v231, s[60:61]
	v_cndmask_b32_e64 v93, v93, v231, s[58:59]
	v_cndmask_b32_e64 v92, v92, v231, s[56:57]
	v_cndmask_b32_e64 v91, v91, v231, s[54:55]
	v_cndmask_b32_e64 v90, v90, v231, s[52:53]
	v_cndmask_b32_e64 v89, v89, v231, s[50:51]
	v_cndmask_b32_e64 v88, v88, v231, s[48:49]
	v_cndmask_b32_e64 v87, v87, v231, s[46:47]
	v_cndmask_b32_e64 v86, v86, v231, s[44:45]
	v_cndmask_b32_e64 v85, v85, v231, s[42:43]
	v_cndmask_b32_e64 v84, v84, v231, s[40:41]
	v_cndmask_b32_e64 v83, v83, v231, s[38:39]
	v_cndmask_b32_e64 v82, v82, v231, s[36:37]
	v_cndmask_b32_e64 v81, v81, v231, s[34:35]
	v_cndmask_b32_e64 v79, v79, v231, s[30:31]
	v_cndmask_b32_e64 v78, v78, v231, s[28:29]
	v_cndmask_b32_e64 v77, v77, v231, s[26:27]
	v_cndmask_b32_e64 v76, v76, v231, s[24:25]
	v_cndmask_b32_e64 v75, v75, v231, s[22:23]
	v_cndmask_b32_e64 v74, v74, v231, s[20:21]
	v_cndmask_b32_e64 v73, v73, v231, s[18:19]
	v_cndmask_b32_e64 v72, v72, v231, s[16:17]
	v_cndmask_b32_e64 v71, v71, v231, s[14:15]
	v_cndmask_b32_e64 v70, v70, v231, s[12:13]
	v_cndmask_b32_e64 v69, v69, v231, s[10:11]
	v_cndmask_b32_e64 v68, v68, v231, s[8:9]
	v_cndmask_b32_e64 v67, v67, v231, s[6:7]
	v_cndmask_b32_e64 v66, v66, v231, s[4:5]
	v_cndmask_b32_e64 v65, v65, v231, s[2:3]
	v_cndmask_b32_e32 v64, v64, v231, vcc

.LBB0_700:
	s_cmp_lt_u32 s80, 3
	v_readlane_b32 s0, v254, 54
	v_readlane_b32 s1, v254, 56
	s_cselect_b32 s78, s0, s1
	v_readlane_b32 s0, v254, 57
	s_or_b32 s88, s78, s0
	s_ashr_i32 s89, s88, 31
	s_lshl_b64 s[0:1], s[88:89], 12
	v_readlane_b32 s2, v254, 34
	s_add_u32 s0, s2, s0
	v_readlane_b32 s2, v254, 36
	s_addc_u32 s1, s2, s1
	s_lshl_b32 s2, s74, 1
	v_or_b32_e32 v64, s73, v168
	s_add_u32 s6, s0, s2
	v_ashrrev_i32_e32 v65, 31, v64
	s_addc_u32 s7, s1, 0
	v_lshlrev_b64 v[64:65], 12, v[64:65]
	v_lshl_add_u64 v[64:65], s[6:7], 0, v[64:65]
	v_lshlrev_b32_e32 v162, 4, v169
	v_lshl_add_u64 v[64:65], v[64:65], 0, v[162:163]
	global_load_dwordx4 v[140:143], v[64:65], off
	global_load_dwordx4 v[136:139], v[64:65], off offset:32
	global_load_dwordx4 v[132:135], v[64:65], off offset:64
	global_load_dwordx4 v[128:131], v[64:65], off offset:96
	global_load_dwordx4 v[124:127], v[64:65], off offset:128
	global_load_dwordx4 v[120:123], v[64:65], off offset:160
	global_load_dwordx4 v[116:119], v[64:65], off offset:192
	global_load_dwordx4 v[112:115], v[64:65], off offset:224
	s_waitcnt lgkmcnt(0)
	s_barrier
	s_setprio 1
	s_cmp_gt_i32 s99, s84
	s_cbranch_scc1 .Lmsk_2
	ds_read_b64_tr_b16 v[64:65], v175 offset:0x4000
	ds_read_b64_tr_b16 v[66:67], v175 offset:0x4800
	ds_read_b64_tr_b16 v[68:69], v175 offset:0x5000
	ds_read_b64_tr_b16 v[70:71], v175 offset:0x5800
	ds_read_b64_tr_b16 v[72:73], v175 offset:0x6000
	ds_read_b64_tr_b16 v[74:75], v175 offset:0x6800
	ds_read_b64_tr_b16 v[76:77], v175 offset:0x7000
	ds_read_b64_tr_b16 v[78:79], v175 offset:0x7800
	ds_read_b64_tr_b16 v[80:81], v175 offset:0x4200
	ds_read_b64_tr_b16 v[82:83], v175 offset:0x4a00
	ds_read_b64_tr_b16 v[84:85], v175 offset:0x5200
	ds_read_b64_tr_b16 v[86:87], v175 offset:0x5a00
	ds_read_b64_tr_b16 v[88:89], v175 offset:0x6200
	ds_read_b64_tr_b16 v[90:91], v175 offset:0x6a00
	ds_read_b64_tr_b16 v[92:93], v175 offset:0x7200
	ds_read_b64_tr_b16 v[94:95], v175 offset:0x7a00
	s_waitcnt lgkmcnt(14)
	s_nop 0
	v_mfma_f32_32x32x16_bf16 v[48:63], v[156:159], v[64:67], v[48:63]
	ds_read_b64_tr_b16 v[64:65], v175 offset:0x4400
	ds_read_b64_tr_b16 v[66:67], v175 offset:0x4c00
	s_waitcnt lgkmcnt(14)
	v_mfma_f32_32x32x16_bf16 v[48:63], v[152:155], v[68:71], v[48:63]
	ds_read_b64_tr_b16 v[68:69], v175 offset:0x5400
	ds_read_b64_tr_b16 v[70:71], v175 offset:0x5c00
	s_waitcnt lgkmcnt(14)
	v_mfma_f32_32x32x16_bf16 v[48:63], v[148:151], v[72:75], v[48:63]
	ds_read_b64_tr_b16 v[72:73], v175 offset:0x6400
	ds_read_b64_tr_b16 v[74:75], v175 offset:0x6c00
	s_waitcnt lgkmcnt(14)
	v_mfma_f32_32x32x16_bf16 v[48:63], v[144:147], v[76:79], v[48:63]
	ds_read_b64_tr_b16 v[76:77], v175 offset:0x7400
	ds_read_b64_tr_b16 v[78:79], v175 offset:0x7c00
	s_waitcnt lgkmcnt(14)
	v_mfma_f32_32x32x16_bf16 v[32:47], v[156:159], v[80:83], v[32:47]
	ds_read_b64_tr_b16 v[80:81], v175 offset:0x4600
	ds_read_b64_tr_b16 v[82:83], v175 offset:0x4e00
	s_waitcnt lgkmcnt(14)
	v_mfma_f32_32x32x16_bf16 v[32:47], v[152:155], v[84:87], v[32:47]
	ds_read_b64_tr_b16 v[84:85], v175 offset:0x5600
	ds_read_b64_tr_b16 v[86:87], v175 offset:0x5e00
	s_waitcnt lgkmcnt(14)
	v_mfma_f32_32x32x16_bf16 v[32:47], v[148:151], v[88:91], v[32:47]
	ds_read_b64_tr_b16 v[88:89], v175 offset:0x6600
	ds_read_b64_tr_b16 v[90:91], v175 offset:0x6e00
	s_waitcnt lgkmcnt(14)
	v_mfma_f32_32x32x16_bf16 v[32:47], v[144:147], v[92:95], v[32:47]
	ds_read_b64_tr_b16 v[92:93], v175 offset:0x7600
	ds_read_b64_tr_b16 v[94:95], v175 offset:0x7e00
	s_waitcnt lgkmcnt(14)
	v_mfma_f32_32x32x16_bf16 v[16:31], v[156:159], v[64:67], v[16:31]
	s_waitcnt lgkmcnt(12)
	v_mfma_f32_32x32x16_bf16 v[16:31], v[152:155], v[68:71], v[16:31]
	s_waitcnt lgkmcnt(10)
	v_mfma_f32_32x32x16_bf16 v[16:31], v[148:151], v[72:75], v[16:31]
	s_waitcnt lgkmcnt(8)
	v_mfma_f32_32x32x16_bf16 v[16:31], v[144:147], v[76:79], v[16:31]
	s_waitcnt lgkmcnt(6)
	v_mfma_f32_32x32x16_bf16 v[0:15], v[156:159], v[80:83], v[0:15]
	s_waitcnt lgkmcnt(4)
	v_mfma_f32_32x32x16_bf16 v[0:15], v[152:155], v[84:87], v[0:15]
	s_waitcnt lgkmcnt(2)
	v_mfma_f32_32x32x16_bf16 v[0:15], v[148:151], v[88:91], v[0:15]
	s_waitcnt lgkmcnt(0)
	v_mfma_f32_32x32x16_bf16 v[0:15], v[144:147], v[92:95], v[0:15]
.Lmsk_2:
	s_setprio 0
	v_readlane_b32 s0, v254, 50
	v_readlane_b32 s1, v254, 51
	s_andn2_b64 vcc, exec, s[0:1]
	s_nop 0
	v_cndmask_b32_e64 v64, 0, 1, s[0:1]
	v_cmp_ne_u32_e64 s[2:3], 1, v64
	s_nop 1
	v_writelane_b32 v255, s2, 23
	s_nop 1
	v_writelane_b32 v255, s3, 24
	s_cbranch_vccnz .LBB0_702
	s_waitcnt lgkmcnt(0)
	s_barrier

.LBB0_743:
	s_waitcnt lgkmcnt(0)
	s_barrier
	s_setprio 1
	s_sub_i32 s100, s79, 64
	s_cmp_gt_i32 s100, s82
	s_cbranch_scc1 .Lmsk_3
	ds_read_b64_tr_b16 v[64:65], v175 offset:0x4000
	ds_read_b64_tr_b16 v[66:67], v175 offset:0x4800
	ds_read_b64_tr_b16 v[68:69], v175 offset:0x5000
	ds_read_b64_tr_b16 v[70:71], v175 offset:0x5800
	ds_read_b64_tr_b16 v[72:73], v175 offset:0x6000
	ds_read_b64_tr_b16 v[74:75], v175 offset:0x6800
	ds_read_b64_tr_b16 v[76:77], v175 offset:0x7000
	ds_read_b64_tr_b16 v[78:79], v175 offset:0x7800
	ds_read_b64_tr_b16 v[80:81], v175 offset:0x4200
	ds_read_b64_tr_b16 v[82:83], v175 offset:0x4a00
	ds_read_b64_tr_b16 v[84:85], v175 offset:0x5200
	ds_read_b64_tr_b16 v[86:87], v175 offset:0x5a00
	ds_read_b64_tr_b16 v[88:89], v175 offset:0x6200
	ds_read_b64_tr_b16 v[90:91], v175 offset:0x6a00
	ds_read_b64_tr_b16 v[92:93], v175 offset:0x7200
	ds_read_b64_tr_b16 v[94:95], v175 offset:0x7a00
	s_waitcnt lgkmcnt(14)
	s_nop 0
	v_mfma_f32_32x32x16_bf16 v[48:63], v[156:159], v[64:67], v[48:63]
	ds_read_b64_tr_b16 v[64:65], v175 offset:0x4400
	ds_read_b64_tr_b16 v[66:67], v175 offset:0x4c00
	s_waitcnt lgkmcnt(14)
	v_mfma_f32_32x32x16_bf16 v[48:63], v[152:155], v[68:71], v[48:63]
	ds_read_b64_tr_b16 v[68:69], v175 offset:0x5400
	ds_read_b64_tr_b16 v[70:71], v175 offset:0x5c00
	s_waitcnt lgkmcnt(14)
	v_mfma_f32_32x32x16_bf16 v[48:63], v[148:151], v[72:75], v[48:63]
	ds_read_b64_tr_b16 v[72:73], v175 offset:0x6400
	ds_read_b64_tr_b16 v[74:75], v175 offset:0x6c00
	s_waitcnt lgkmcnt(14)
	v_mfma_f32_32x32x16_bf16 v[48:63], v[144:147], v[76:79], v[48:63]
	ds_read_b64_tr_b16 v[76:77], v175 offset:0x7400
	ds_read_b64_tr_b16 v[78:79], v175 offset:0x7c00
	s_waitcnt lgkmcnt(14)
	v_mfma_f32_32x32x16_bf16 v[32:47], v[156:159], v[80:83], v[32:47]
	ds_read_b64_tr_b16 v[80:81], v175 offset:0x4600
	ds_read_b64_tr_b16 v[82:83], v175 offset:0x4e00
	s_waitcnt lgkmcnt(14)
	v_mfma_f32_32x32x16_bf16 v[32:47], v[152:155], v[84:87], v[32:47]
	ds_read_b64_tr_b16 v[84:85], v175 offset:0x5600
	ds_read_b64_tr_b16 v[86:87], v175 offset:0x5e00
	s_waitcnt lgkmcnt(14)
	v_mfma_f32_32x32x16_bf16 v[32:47], v[148:151], v[88:91], v[32:47]
	ds_read_b64_tr_b16 v[88:89], v175 offset:0x6600
	ds_read_b64_tr_b16 v[90:91], v175 offset:0x6e00
	s_waitcnt lgkmcnt(14)
	v_mfma_f32_32x32x16_bf16 v[32:47], v[144:147], v[92:95], v[32:47]
	ds_read_b64_tr_b16 v[92:93], v175 offset:0x7600
	ds_read_b64_tr_b16 v[94:95], v175 offset:0x7e00
	s_waitcnt lgkmcnt(14)
	v_mfma_f32_32x32x16_bf16 v[16:31], v[156:159], v[64:67], v[16:31]
	ds_read_b128 v[64:67], v183 offset:0x8000
	s_waitcnt lgkmcnt(13)
	v_mfma_f32_32x32x16_bf16 v[16:31], v[152:155], v[68:71], v[16:31]
	ds_read_b128 v[68:71], v183 offset:0xa000
	s_waitcnt lgkmcnt(12)
	v_mfma_f32_32x32x16_bf16 v[16:31], v[148:151], v[72:75], v[16:31]
	ds_read_b128 v[188:191], v182 offset:0x8000
	s_waitcnt lgkmcnt(11)
	v_mfma_f32_32x32x16_bf16 v[16:31], v[144:147], v[76:79], v[16:31]
	ds_read_b128 v[192:195], v182 offset:0xa000
	s_waitcnt lgkmcnt(10)
	v_mfma_f32_32x32x16_bf16 v[0:15], v[156:159], v[80:83], v[0:15]
	ds_read_b128 v[156:159], v181 offset:0x8000
	s_waitcnt lgkmcnt(9)
	v_mfma_f32_32x32x16_bf16 v[0:15], v[152:155], v[84:87], v[0:15]
	ds_read_b128 v[152:155], v181 offset:0xa000
	s_waitcnt lgkmcnt(8)
	v_mfma_f32_32x32x16_bf16 v[0:15], v[148:151], v[88:91], v[0:15]
	ds_read_b128 v[148:151], v178 offset:0x8000
	s_waitcnt lgkmcnt(7)
	v_mfma_f32_32x32x16_bf16 v[0:15], v[144:147], v[92:95], v[0:15]
	ds_read_b128 v[144:147], v178 offset:0xa000
	s_waitcnt lgkmcnt(7)
	v_mfma_f32_32x32x16_bf16 v[80:95], v[64:67], v[140:143], 0
	ds_read_b128 v[196:199], v176 offset:0x8000
	s_waitcnt lgkmcnt(7)
	v_mfma_f32_32x32x16_bf16 v[64:79], v[68:71], v[140:143], 0
	ds_read_b128 v[200:203], v176 offset:0xa000
	s_waitcnt lgkmcnt(7)
	v_mfma_f32_32x32x16_bf16 v[80:95], v[188:191], v[136:139], v[80:95]
	ds_read_b128 v[188:191], v177 offset:0x8000
	s_waitcnt lgkmcnt(7)
	v_mfma_f32_32x32x16_bf16 v[64:79], v[192:195], v[136:139], v[64:79]
	ds_read_b128 v[192:195], v177 offset:0xa000
	s_waitcnt lgkmcnt(7)
	v_mfma_f32_32x32x16_bf16 v[80:95], v[156:159], v[132:135], v[80:95]
	ds_read_b128 v[156:159], v179 offset:0x8000
	s_waitcnt lgkmcnt(7)
	v_mfma_f32_32x32x16_bf16 v[64:79], v[152:155], v[132:135], v[64:79]
	ds_read_b128 v[152:155], v179 offset:0xa000
	s_waitcnt lgkmcnt(7)
	v_mfma_f32_32x32x16_bf16 v[80:95], v[148:151], v[128:131], v[80:95]
	ds_read_b128 v[148:151], v180 offset:0x8000
	s_waitcnt lgkmcnt(7)
	v_mfma_f32_32x32x16_bf16 v[64:79], v[144:147], v[128:131], v[64:79]
	ds_read_b128 v[144:147], v180 offset:0xa000
	s_waitcnt lgkmcnt(7)
	v_mfma_f32_32x32x16_bf16 v[80:95], v[196:199], v[124:127], v[80:95]
	s_waitcnt lgkmcnt(6)
	v_mfma_f32_32x32x16_bf16 v[64:79], v[200:203], v[124:127], v[64:79]
	s_waitcnt lgkmcnt(5)
	v_mfma_f32_32x32x16_bf16 v[80:95], v[188:191], v[120:123], v[80:95]
	s_waitcnt lgkmcnt(4)
	v_mfma_f32_32x32x16_bf16 v[64:79], v[192:195], v[120:123], v[64:79]
	s_waitcnt lgkmcnt(3)
	v_mfma_f32_32x32x16_bf16 v[80:95], v[156:159], v[116:119], v[80:95]
	s_waitcnt lgkmcnt(2)
	v_mfma_f32_32x32x16_bf16 v[64:79], v[152:155], v[116:119], v[64:79]
	s_waitcnt lgkmcnt(1)
	v_mfma_f32_32x32x16_bf16 v[80:95], v[148:151], v[112:115], v[80:95]
	s_waitcnt lgkmcnt(0)
	v_mfma_f32_32x32x16_bf16 v[64:79], v[144:147], v[112:115], v[64:79]
.Lmsk_3:
	s_setprio 0
	s_waitcnt lgkmcnt(0)
	s_barrier
	s_cmp_le_i32 s79, s82
	s_mov_b64 s[4:5], -1
	s_cbranch_scc0 .LBB0_747
	s_add_i32 s4, s79, 63
	s_cmp_le_i32 s4, s82
	s_cbranch_scc1 .LBB0_746
	v_cmp_gt_i32_e64 s[62:63], 26, v186
	v_cmp_gt_i32_e64 s[64:65], 27, v186
	v_cmp_gt_i32_e64 s[60:61], 25, v186
	s_and_b64 s[62:63], s[64:65], s[62:63]
	v_cmp_gt_i32_e64 s[58:59], 24, v186
	s_and_b64 s[60:61], s[62:63], s[60:61]
	v_cmp_gt_i32_e64 s[56:57], 19, v186
	s_and_b64 s[58:59], s[60:61], s[58:59]
	v_cmp_gt_i32_e64 s[54:55], 18, v186
	s_and_b64 s[56:57], s[58:59], s[56:57]
	v_cmp_gt_i32_e64 s[52:53], 17, v186
	s_and_b64 s[54:55], s[56:57], s[54:55]
	v_cmp_gt_i32_e64 s[50:51], 16, v186
	s_and_b64 s[52:53], s[54:55], s[52:53]
	v_cmp_gt_i32_e64 s[48:49], 11, v186
	s_and_b64 s[50:51], s[52:53], s[50:51]
	v_cmp_gt_i32_e64 s[46:47], 10, v186
	s_and_b64 s[48:49], s[50:51], s[48:49]
	v_cmp_gt_i32_e64 s[44:45], 9, v186
	s_and_b64 s[46:47], s[48:49], s[46:47]
	v_cmp_gt_i32_e64 s[42:43], 8, v186
	s_and_b64 s[44:45], s[46:47], s[44:45]
	v_cmp_gt_i32_e64 s[40:41], 3, v186
	s_and_b64 s[42:43], s[44:45], s[42:43]
	v_cmp_gt_i32_e64 s[38:39], 2, v186
	s_and_b64 s[40:41], s[42:43], s[40:41]
	v_cmp_gt_i32_e64 s[36:37], 1, v186
	s_and_b64 s[38:39], s[40:41], s[38:39]
	v_cmp_gt_i32_e64 s[34:35], 0, v186
	s_and_b64 s[36:37], s[38:39], s[36:37]
	s_and_b64 s[34:35], s[36:37], s[34:35]
	v_cmp_gt_i32_e64 s[30:31], 58, v186
	v_cndmask_b32_e64 v80, v80, v231, s[34:35]
	v_cmp_gt_i32_e64 s[34:35], 59, v186
	v_cmp_gt_i32_e64 s[28:29], 57, v186
	s_and_b64 s[30:31], s[34:35], s[30:31]
	v_cmp_gt_i32_e64 s[26:27], 56, v186
	s_and_b64 s[28:29], s[30:31], s[28:29]
	v_cmp_gt_i32_e64 s[24:25], 51, v186
	s_and_b64 s[26:27], s[28:29], s[26:27]
	v_cmp_gt_i32_e64 s[22:23], 50, v186
	s_and_b64 s[24:25], s[26:27], s[24:25]
	v_cmp_gt_i32_e64 s[20:21], 49, v186
	s_and_b64 s[22:23], s[24:25], s[22:23]
	v_cmp_gt_i32_e64 s[18:19], 48, v186
	s_and_b64 s[20:21], s[22:23], s[20:21]
	v_cmp_gt_i32_e64 s[16:17], 43, v186
	s_and_b64 s[18:19], s[20:21], s[18:19]
	v_cmp_gt_i32_e64 s[14:15], 42, v186
	s_and_b64 s[16:17], s[18:19], s[16:17]
	v_cmp_gt_i32_e64 s[12:13], 41, v186
	s_and_b64 s[14:15], s[16:17], s[14:15]
	v_cmp_gt_i32_e64 s[10:11], 40, v186
	s_and_b64 s[12:13], s[14:15], s[12:13]
	v_cmp_gt_i32_e64 s[8:9], 35, v186
	s_and_b64 s[10:11], s[12:13], s[10:11]
	v_cmp_gt_i32_e64 s[6:7], 34, v186
	s_and_b64 s[8:9], s[10:11], s[8:9]
	v_cmp_gt_i32_e64 s[4:5], 33, v186
	s_and_b64 s[6:7], s[8:9], s[6:7]
	v_cmp_gt_i32_e32 vcc, 32, v186
	s_and_b64 s[4:5], s[6:7], s[4:5]
	s_and_b64 vcc, s[4:5], vcc
	v_cndmask_b32_e64 v95, v95, v231, s[64:65]
	v_cndmask_b32_e64 v94, v94, v231, s[62:63]
	v_cndmask_b32_e64 v93, v93, v231, s[60:61]
	v_cndmask_b32_e64 v92, v92, v231, s[58:59]
	v_cndmask_b32_e64 v91, v91, v231, s[56:57]
	v_cndmask_b32_e64 v90, v90, v231, s[54:55]
	v_cndmask_b32_e64 v89, v89, v231, s[52:53]
	v_cndmask_b32_e64 v88, v88, v231, s[50:51]
	v_cndmask_b32_e64 v87, v87, v231, s[48:49]
	v_cndmask_b32_e64 v86, v86, v231, s[46:47]
	v_cndmask_b32_e64 v85, v85, v231, s[44:45]
	v_cndmask_b32_e64 v84, v84, v231, s[42:43]
	v_cndmask_b32_e64 v83, v83, v231, s[40:41]
	v_cndmask_b32_e64 v82, v82, v231, s[38:39]
	v_cndmask_b32_e64 v81, v81, v231, s[36:37]
	v_cndmask_b32_e64 v79, v79, v231, s[34:35]
	v_cndmask_b32_e64 v78, v78, v231, s[30:31]
	v_cndmask_b32_e64 v77, v77, v231, s[28:29]
	v_cndmask_b32_e64 v76, v76, v231, s[26:27]
	v_cndmask_b32_e64 v75, v75, v231, s[24:25]
	v_cndmask_b32_e64 v74, v74, v231, s[22:23]
	v_cndmask_b32_e64 v73, v73, v231, s[20:21]
	v_cndmask_b32_e64 v72, v72, v231, s[18:19]
	v_cndmask_b32_e64 v71, v71, v231, s[16:17]
	v_cndmask_b32_e64 v70, v70, v231, s[14:15]
	v_cndmask_b32_e64 v69, v69, v231, s[12:13]
	v_cndmask_b32_e64 v68, v68, v231, s[10:11]
	v_cndmask_b32_e64 v67, v67, v231, s[8:9]
	v_cndmask_b32_e64 v66, v66, v231, s[6:7]
	v_cndmask_b32_e64 v65, v65, v231, s[4:5]
	v_cndmask_b32_e32 v64, v64, v231, vcc

.LBB0_755:
	s_setprio 1
	s_sub_i32 s99, s79, 64
	s_sub_i32 s100, s79, 0x80
	s_cmp_gt_i32 s100, s82
	s_cbranch_scc1 .Lmsk_4
	ds_read_b64_tr_b16 v[64:65], v175 offset:0
	ds_read_b64_tr_b16 v[66:67], v175 offset:0x800
	ds_read_b64_tr_b16 v[68:69], v175 offset:0x1000
	ds_read_b64_tr_b16 v[70:71], v175 offset:0x1800
	ds_read_b64_tr_b16 v[72:73], v175 offset:0x2000
	ds_read_b64_tr_b16 v[74:75], v175 offset:0x2800
	ds_read_b64_tr_b16 v[76:77], v175 offset:0x3000
	ds_read_b64_tr_b16 v[78:79], v175 offset:0x3800
	ds_read_b64_tr_b16 v[80:81], v175 offset:0x200
	ds_read_b64_tr_b16 v[82:83], v175 offset:0xa00
	ds_read_b64_tr_b16 v[84:85], v175 offset:0x1200
	ds_read_b64_tr_b16 v[86:87], v175 offset:0x1a00
	ds_read_b64_tr_b16 v[88:89], v175 offset:0x2200
	ds_read_b64_tr_b16 v[90:91], v175 offset:0x2a00
	ds_read_b64_tr_b16 v[92:93], v175 offset:0x3200
	ds_read_b64_tr_b16 v[94:95], v175 offset:0x3a00
	s_waitcnt lgkmcnt(14)
	s_nop 0
	v_mfma_f32_32x32x16_bf16 v[48:63], v[156:159], v[64:67], v[48:63]
	ds_read_b64_tr_b16 v[64:65], v175 offset:0x400
	ds_read_b64_tr_b16 v[66:67], v175 offset:0xc00
	s_waitcnt lgkmcnt(14)
	v_mfma_f32_32x32x16_bf16 v[48:63], v[152:155], v[68:71], v[48:63]
	ds_read_b64_tr_b16 v[68:69], v175 offset:0x1400
	ds_read_b64_tr_b16 v[70:71], v175 offset:0x1c00
	s_waitcnt lgkmcnt(14)
	v_mfma_f32_32x32x16_bf16 v[48:63], v[148:151], v[72:75], v[48:63]
	ds_read_b64_tr_b16 v[72:73], v175 offset:0x2400
	ds_read_b64_tr_b16 v[74:75], v175 offset:0x2c00
	s_waitcnt lgkmcnt(14)
	v_mfma_f32_32x32x16_bf16 v[48:63], v[144:147], v[76:79], v[48:63]
	ds_read_b64_tr_b16 v[76:77], v175 offset:0x3400
	ds_read_b64_tr_b16 v[78:79], v175 offset:0x3c00
	s_waitcnt lgkmcnt(14)
	v_mfma_f32_32x32x16_bf16 v[32:47], v[156:159], v[80:83], v[32:47]
	ds_read_b64_tr_b16 v[80:81], v175 offset:0x600
	ds_read_b64_tr_b16 v[82:83], v175 offset:0xe00
	s_waitcnt lgkmcnt(14)
	v_mfma_f32_32x32x16_bf16 v[32:47], v[152:155], v[84:87], v[32:47]
	ds_read_b64_tr_b16 v[84:85], v175 offset:0x1600
	ds_read_b64_tr_b16 v[86:87], v175 offset:0x1e00
	s_waitcnt lgkmcnt(14)
	v_mfma_f32_32x32x16_bf16 v[32:47], v[148:151], v[88:91], v[32:47]
	ds_read_b64_tr_b16 v[88:89], v175 offset:0x2600
	ds_read_b64_tr_b16 v[90:91], v175 offset:0x2e00
	s_waitcnt lgkmcnt(14)
	v_mfma_f32_32x32x16_bf16 v[32:47], v[144:147], v[92:95], v[32:47]
	ds_read_b64_tr_b16 v[92:93], v175 offset:0x3600
	ds_read_b64_tr_b16 v[94:95], v175 offset:0x3e00
	s_waitcnt lgkmcnt(14)
	v_mfma_f32_32x32x16_bf16 v[16:31], v[156:159], v[64:67], v[16:31]
	ds_read_b128 v[64:67], v183 offset:0xc000
	s_waitcnt lgkmcnt(13)
	v_mfma_f32_32x32x16_bf16 v[16:31], v[152:155], v[68:71], v[16:31]
	ds_read_b128 v[68:71], v183 offset:0xe000
	s_waitcnt lgkmcnt(12)
	v_mfma_f32_32x32x16_bf16 v[16:31], v[148:151], v[72:75], v[16:31]
	ds_read_b128 v[186:189], v182 offset:0xc000
	s_waitcnt lgkmcnt(11)
	v_mfma_f32_32x32x16_bf16 v[16:31], v[144:147], v[76:79], v[16:31]
	ds_read_b128 v[190:193], v182 offset:0xe000
	s_waitcnt lgkmcnt(10)
	v_mfma_f32_32x32x16_bf16 v[0:15], v[156:159], v[80:83], v[0:15]
	ds_read_b128 v[156:159], v181 offset:0xc000
	s_waitcnt lgkmcnt(9)
	v_mfma_f32_32x32x16_bf16 v[0:15], v[152:155], v[84:87], v[0:15]
	ds_read_b128 v[152:155], v181 offset:0xe000
	s_waitcnt lgkmcnt(8)
	v_mfma_f32_32x32x16_bf16 v[0:15], v[148:151], v[88:91], v[0:15]
	ds_read_b128 v[148:151], v178 offset:0xc000
	s_waitcnt lgkmcnt(7)
	v_mfma_f32_32x32x16_bf16 v[0:15], v[144:147], v[92:95], v[0:15]
	ds_read_b128 v[144:147], v178 offset:0xe000
	s_waitcnt lgkmcnt(7)
	v_mfma_f32_32x32x16_bf16 v[80:95], v[64:67], v[140:143], 0
	ds_read_b128 v[194:197], v176 offset:0xc000
	s_waitcnt lgkmcnt(7)
	v_mfma_f32_32x32x16_bf16 v[64:79], v[68:71], v[140:143], 0
	ds_read_b128 v[140:143], v176 offset:0xe000
	s_waitcnt lgkmcnt(7)
	v_mfma_f32_32x32x16_bf16 v[80:95], v[186:189], v[136:139], v[80:95]
	ds_read_b128 v[186:189], v177 offset:0xc000
	s_waitcnt lgkmcnt(7)
	v_mfma_f32_32x32x16_bf16 v[64:79], v[190:193], v[136:139], v[64:79]
	ds_read_b128 v[136:139], v177 offset:0xe000
	s_waitcnt lgkmcnt(7)
	v_mfma_f32_32x32x16_bf16 v[80:95], v[156:159], v[132:135], v[80:95]
	ds_read_b128 v[156:159], v179 offset:0xc000
	s_waitcnt lgkmcnt(7)
	v_mfma_f32_32x32x16_bf16 v[64:79], v[152:155], v[132:135], v[64:79]
	ds_read_b128 v[132:135], v179 offset:0xe000
	s_waitcnt lgkmcnt(7)
	v_mfma_f32_32x32x16_bf16 v[80:95], v[148:151], v[128:131], v[80:95]
	ds_read_b128 v[148:151], v180 offset:0xc000
	s_waitcnt lgkmcnt(7)
	v_mfma_f32_32x32x16_bf16 v[64:79], v[144:147], v[128:131], v[64:79]
	ds_read_b128 v[128:131], v180 offset:0xe000
	s_waitcnt lgkmcnt(7)
	v_mfma_f32_32x32x16_bf16 v[80:95], v[194:197], v[124:127], v[80:95]
	s_waitcnt lgkmcnt(6)
	v_mfma_f32_32x32x16_bf16 v[64:79], v[140:143], v[124:127], v[64:79]
	s_waitcnt lgkmcnt(5)
	v_mfma_f32_32x32x16_bf16 v[80:95], v[186:189], v[120:123], v[80:95]
	s_waitcnt lgkmcnt(4)
	v_mfma_f32_32x32x16_bf16 v[64:79], v[136:139], v[120:123], v[64:79]
	s_waitcnt lgkmcnt(3)
	v_mfma_f32_32x32x16_bf16 v[80:95], v[156:159], v[116:119], v[80:95]
	s_waitcnt lgkmcnt(2)
	v_mfma_f32_32x32x16_bf16 v[64:79], v[132:135], v[116:119], v[64:79]
	s_waitcnt lgkmcnt(1)
	v_mfma_f32_32x32x16_bf16 v[80:95], v[148:151], v[112:115], v[80:95]
	s_waitcnt lgkmcnt(0)
	v_mfma_f32_32x32x16_bf16 v[64:79], v[128:131], v[112:115], v[64:79]
.Lmsk_4:
	s_setprio 0
	s_waitcnt lgkmcnt(0)
	s_barrier
	s_and_b32 s1, s78, 0xffffffc0
	s_add_i32 s0, s1, 0xc0
	s_cmp_le_i32 s0, s82
	s_mov_b64 s[4:5], -1
	s_mov_b32 s33, s85
	s_mov_b32 s79, 0x7ffffc
	s_cbranch_scc0 .LBB0_759
	s_addk_i32 s1, 0xff
	s_cmp_le_i32 s1, s82
	s_cbranch_scc1 .LBB0_758
	v_subrev_u32_e32 v112, s0, v185
	v_cmp_gt_i32_e64 s[62:63], 26, v112
	v_cmp_gt_i32_e64 s[64:65], 27, v112
	v_cmp_gt_i32_e64 s[60:61], 25, v112
	s_and_b64 s[62:63], s[64:65], s[62:63]
	v_cmp_gt_i32_e64 s[58:59], 24, v112
	s_and_b64 s[60:61], s[62:63], s[60:61]
	v_cmp_gt_i32_e64 s[56:57], 19, v112
	s_and_b64 s[58:59], s[60:61], s[58:59]
	v_cmp_gt_i32_e64 s[54:55], 18, v112
	s_and_b64 s[56:57], s[58:59], s[56:57]
	v_cmp_gt_i32_e64 s[52:53], 17, v112
	s_and_b64 s[54:55], s[56:57], s[54:55]
	v_cmp_gt_i32_e64 s[50:51], 16, v112
	s_and_b64 s[52:53], s[54:55], s[52:53]
	v_cmp_gt_i32_e64 s[48:49], 11, v112
	s_and_b64 s[50:51], s[52:53], s[50:51]
	v_cmp_gt_i32_e64 s[46:47], 10, v112
	s_and_b64 s[48:49], s[50:51], s[48:49]
	v_cmp_gt_i32_e64 s[44:45], 9, v112
	s_and_b64 s[46:47], s[48:49], s[46:47]
	v_cmp_gt_i32_e64 s[42:43], 8, v112
	s_and_b64 s[44:45], s[46:47], s[44:45]
	v_cmp_gt_i32_e64 s[40:41], 3, v112
	s_and_b64 s[42:43], s[44:45], s[42:43]
	v_cmp_gt_i32_e64 s[38:39], 2, v112
	s_and_b64 s[40:41], s[42:43], s[40:41]
	v_cmp_gt_i32_e64 s[36:37], 1, v112
	s_and_b64 s[38:39], s[40:41], s[38:39]
	v_cmp_gt_i32_e64 s[34:35], 0, v112
	s_and_b64 s[36:37], s[38:39], s[36:37]
	s_and_b64 s[34:35], s[36:37], s[34:35]
	v_cmp_gt_i32_e64 s[30:31], 58, v112
	v_cndmask_b32_e64 v80, v80, v231, s[34:35]
	v_cmp_gt_i32_e64 s[34:35], 59, v112
	v_cmp_gt_i32_e64 s[28:29], 57, v112
	s_and_b64 s[30:31], s[34:35], s[30:31]
	v_cmp_gt_i32_e64 s[26:27], 56, v112
	s_and_b64 s[28:29], s[30:31], s[28:29]
	v_cmp_gt_i32_e64 s[24:25], 51, v112
	s_and_b64 s[26:27], s[28:29], s[26:27]
	v_cmp_gt_i32_e64 s[22:23], 50, v112
	s_and_b64 s[24:25], s[26:27], s[24:25]
	v_cmp_gt_i32_e64 s[20:21], 49, v112
	s_and_b64 s[22:23], s[24:25], s[22:23]
	v_cmp_gt_i32_e64 s[18:19], 48, v112
	s_and_b64 s[20:21], s[22:23], s[20:21]
	v_cmp_gt_i32_e64 s[16:17], 43, v112
	s_and_b64 s[18:19], s[20:21], s[18:19]
	v_cmp_gt_i32_e64 s[14:15], 42, v112
	s_and_b64 s[16:17], s[18:19], s[16:17]
	v_cmp_gt_i32_e64 s[12:13], 41, v112
	s_and_b64 s[14:15], s[16:17], s[14:15]
	v_cmp_gt_i32_e64 s[10:11], 40, v112
	s_and_b64 s[12:13], s[14:15], s[12:13]
	v_cmp_gt_i32_e64 s[8:9], 35, v112
	s_and_b64 s[10:11], s[12:13], s[10:11]
	v_cmp_gt_i32_e64 s[6:7], 34, v112
	s_and_b64 s[8:9], s[10:11], s[8:9]
	v_cmp_gt_i32_e64 s[4:5], 33, v112
	s_and_b64 s[6:7], s[8:9], s[6:7]
	v_cmp_gt_i32_e32 vcc, 32, v112
	s_and_b64 s[4:5], s[6:7], s[4:5]
	s_and_b64 vcc, s[4:5], vcc
	v_cndmask_b32_e64 v95, v95, v231, s[64:65]
	v_cndmask_b32_e64 v94, v94, v231, s[62:63]
	v_cndmask_b32_e64 v93, v93, v231, s[60:61]
	v_cndmask_b32_e64 v92, v92, v231, s[58:59]
	v_cndmask_b32_e64 v91, v91, v231, s[56:57]
	v_cndmask_b32_e64 v90, v90, v231, s[54:55]
	v_cndmask_b32_e64 v89, v89, v231, s[52:53]
	v_cndmask_b32_e64 v88, v88, v231, s[50:51]
	v_cndmask_b32_e64 v87, v87, v231, s[48:49]
	v_cndmask_b32_e64 v86, v86, v231, s[46:47]
	v_cndmask_b32_e64 v85, v85, v231, s[44:45]
	v_cndmask_b32_e64 v84, v84, v231, s[42:43]
	v_cndmask_b32_e64 v83, v83, v231, s[40:41]
	v_cndmask_b32_e64 v82, v82, v231, s[38:39]
	v_cndmask_b32_e64 v81, v81, v231, s[36:37]
	v_cndmask_b32_e64 v79, v79, v231, s[34:35]
	v_cndmask_b32_e64 v78, v78, v231, s[30:31]
	v_cndmask_b32_e64 v77, v77, v231, s[28:29]
	v_cndmask_b32_e64 v76, v76, v231, s[26:27]
	v_cndmask_b32_e64 v75, v75, v231, s[24:25]
	v_cndmask_b32_e64 v74, v74, v231, s[22:23]
	v_cndmask_b32_e64 v73, v73, v231, s[20:21]
	v_cndmask_b32_e64 v72, v72, v231, s[18:19]
	v_cndmask_b32_e64 v71, v71, v231, s[16:17]
	v_cndmask_b32_e64 v70, v70, v231, s[14:15]
	v_cndmask_b32_e64 v69, v69, v231, s[12:13]
	v_cndmask_b32_e64 v68, v68, v231, s[10:11]
	v_cndmask_b32_e64 v67, v67, v231, s[8:9]
	v_cndmask_b32_e64 v66, v66, v231, s[6:7]
	v_cndmask_b32_e64 v65, v65, v231, s[4:5]
	v_cndmask_b32_e32 v64, v64, v231, vcc

.LBB0_765:
	v_or_b32_e32 v64, s87, v165
	v_ashrrev_i32_e32 v65, 31, v64
	v_lshlrev_b64 v[64:65], 12, v[64:65]
	v_lshl_add_u64 v[64:65], s[70:71], 0, v[64:65]
	v_lshlrev_b32_e32 v162, 4, v169
	v_lshl_add_u64 v[64:65], v[64:65], 0, v[162:163]
	global_load_dwordx4 v[140:143], v[64:65], off
	global_load_dwordx4 v[136:139], v[64:65], off offset:32
	global_load_dwordx4 v[132:135], v[64:65], off offset:64
	global_load_dwordx4 v[128:131], v[64:65], off offset:96
	global_load_dwordx4 v[124:127], v[64:65], off offset:128
	global_load_dwordx4 v[120:123], v[64:65], off offset:160
	global_load_dwordx4 v[116:119], v[64:65], off offset:192
	global_load_dwordx4 v[112:115], v[64:65], off offset:224
	s_waitcnt lgkmcnt(0)
	s_barrier
	s_movk_i32 s20, 0xe0
	s_setprio 1
	s_cmp_gt_i32 s99, s82
	s_cbranch_scc1 .Lmsk_5
	ds_read_b64_tr_b16 v[64:65], v175 offset:0x4000
	ds_read_b64_tr_b16 v[66:67], v175 offset:0x4800
	ds_read_b64_tr_b16 v[68:69], v175 offset:0x5000
	ds_read_b64_tr_b16 v[70:71], v175 offset:0x5800
	ds_read_b64_tr_b16 v[72:73], v175 offset:0x6000
	ds_read_b64_tr_b16 v[74:75], v175 offset:0x6800
	ds_read_b64_tr_b16 v[76:77], v175 offset:0x7000
	ds_read_b64_tr_b16 v[78:79], v175 offset:0x7800
	ds_read_b64_tr_b16 v[80:81], v175 offset:0x4200
	ds_read_b64_tr_b16 v[82:83], v175 offset:0x4a00
	ds_read_b64_tr_b16 v[84:85], v175 offset:0x5200
	ds_read_b64_tr_b16 v[86:87], v175 offset:0x5a00
	ds_read_b64_tr_b16 v[88:89], v175 offset:0x6200
	ds_read_b64_tr_b16 v[90:91], v175 offset:0x6a00
	ds_read_b64_tr_b16 v[92:93], v175 offset:0x7200
	ds_read_b64_tr_b16 v[94:95], v175 offset:0x7a00
	s_waitcnt lgkmcnt(14)
	s_nop 0
	v_mfma_f32_32x32x16_bf16 v[48:63], v[156:159], v[64:67], v[48:63]
	ds_read_b64_tr_b16 v[64:65], v175 offset:0x4400
	ds_read_b64_tr_b16 v[66:67], v175 offset:0x4c00
	s_waitcnt lgkmcnt(14)
	v_mfma_f32_32x32x16_bf16 v[48:63], v[152:155], v[68:71], v[48:63]
	ds_read_b64_tr_b16 v[68:69], v175 offset:0x5400
	ds_read_b64_tr_b16 v[70:71], v175 offset:0x5c00
	s_waitcnt lgkmcnt(14)
	v_mfma_f32_32x32x16_bf16 v[48:63], v[148:151], v[72:75], v[48:63]
	ds_read_b64_tr_b16 v[72:73], v175 offset:0x6400
	ds_read_b64_tr_b16 v[74:75], v175 offset:0x6c00
	s_waitcnt lgkmcnt(14)
	v_mfma_f32_32x32x16_bf16 v[48:63], v[144:147], v[76:79], v[48:63]
	ds_read_b64_tr_b16 v[76:77], v175 offset:0x7400
	ds_read_b64_tr_b16 v[78:79], v175 offset:0x7c00
	s_waitcnt lgkmcnt(14)
	v_mfma_f32_32x32x16_bf16 v[32:47], v[156:159], v[80:83], v[32:47]
	ds_read_b64_tr_b16 v[80:81], v175 offset:0x4600
	ds_read_b64_tr_b16 v[82:83], v175 offset:0x4e00
	s_waitcnt lgkmcnt(14)
	v_mfma_f32_32x32x16_bf16 v[32:47], v[152:155], v[84:87], v[32:47]
	ds_read_b64_tr_b16 v[84:85], v175 offset:0x5600
	ds_read_b64_tr_b16 v[86:87], v175 offset:0x5e00
	s_waitcnt lgkmcnt(14)
	v_mfma_f32_32x32x16_bf16 v[32:47], v[148:151], v[88:91], v[32:47]
	ds_read_b64_tr_b16 v[88:89], v175 offset:0x6600
	ds_read_b64_tr_b16 v[90:91], v175 offset:0x6e00
	s_waitcnt lgkmcnt(14)
	v_mfma_f32_32x32x16_bf16 v[32:47], v[144:147], v[92:95], v[32:47]
	ds_read_b64_tr_b16 v[92:93], v175 offset:0x7600
	ds_read_b64_tr_b16 v[94:95], v175 offset:0x7e00
	s_waitcnt lgkmcnt(14)
	v_mfma_f32_32x32x16_bf16 v[16:31], v[156:159], v[64:67], v[16:31]
	s_waitcnt lgkmcnt(12)
	v_mfma_f32_32x32x16_bf16 v[16:31], v[152:155], v[68:71], v[16:31]
	s_waitcnt lgkmcnt(10)
	v_mfma_f32_32x32x16_bf16 v[16:31], v[148:151], v[72:75], v[16:31]
	s_waitcnt lgkmcnt(8)
	v_mfma_f32_32x32x16_bf16 v[16:31], v[144:147], v[76:79], v[16:31]
	s_waitcnt lgkmcnt(6)
	v_mfma_f32_32x32x16_bf16 v[0:15], v[156:159], v[80:83], v[0:15]
	s_waitcnt lgkmcnt(4)
	v_mfma_f32_32x32x16_bf16 v[0:15], v[152:155], v[84:87], v[0:15]
	s_waitcnt lgkmcnt(2)
	v_mfma_f32_32x32x16_bf16 v[0:15], v[148:151], v[88:91], v[0:15]
	s_waitcnt lgkmcnt(0)
	v_mfma_f32_32x32x16_bf16 v[0:15], v[144:147], v[92:95], v[0:15]
.Lmsk_5:
	s_setprio 0
	v_readlane_b32 s0, v255, 23
	v_readlane_b32 s1, v255, 24
	s_and_b64 vcc, exec, s[0:1]
	s_cbranch_vccnz .LBB0_767
	s_waitcnt lgkmcnt(0)
	s_barrier

	.amdhsa_kernel _Z6mk_fwd4Args
		.amdhsa_group_segment_fixed_size 0
		.amdhsa_private_segment_fixed_size 0
		.amdhsa_kernarg_size 432
		.amdhsa_user_sgpr_count 2
		.amdhsa_user_sgpr_dispatch_ptr 0
		.amdhsa_user_sgpr_queue_ptr 0
		.amdhsa_user_sgpr_kernarg_segment_ptr 1
		.amdhsa_user_sgpr_dispatch_id 0
		.amdhsa_user_sgpr_kernarg_preload_length 0
		.amdhsa_user_sgpr_kernarg_preload_offset 0
		.amdhsa_user_sgpr_private_segment_size 0
		.amdhsa_uses_dynamic_stack 0
		.amdhsa_enable_private_segment 0
		.amdhsa_system_sgpr_workgroup_id_x 1
		.amdhsa_system_sgpr_workgroup_id_y 0
		.amdhsa_system_sgpr_workgroup_id_z 0
		.amdhsa_system_sgpr_workgroup_info 0
		.amdhsa_system_vgpr_workitem_id 2
		.amdhsa_next_free_vgpr 256
		.amdhsa_next_free_sgpr 102
		.amdhsa_accum_offset 256
		.amdhsa_reserve_vcc 1
		.amdhsa_float_round_mode_32 0
		.amdhsa_float_round_mode_16_64 0
		.amdhsa_float_denorm_mode_32 3
		.amdhsa_float_denorm_mode_16_64 3
		.amdhsa_dx10_clamp 1
		.amdhsa_ieee_mode 1
		.amdhsa_fp16_overflow 0
		.amdhsa_tg_split 0
		.amdhsa_exception_fp_ieee_invalid_op 0
		.amdhsa_exception_fp_denorm_src 0
		.amdhsa_exception_fp_ieee_div_zero 0
		.amdhsa_exception_fp_ieee_overflow 0
		.amdhsa_exception_fp_ieee_underflow 0
		.amdhsa_exception_fp_ieee_inexact 0
		.amdhsa_exception_int_div_zero 0
	.end_amdhsa_kernel

amdhsa.kernels:
  - .agpr_count:     0
    .args:
      - .offset:         0
        .size:           176
        .value_kind:     by_value
      - .offset:         176
        .size:           4
        .value_kind:     hidden_block_count_x
      - .offset:         180
        .size:           4
        .value_kind:     hidden_block_count_y
      - .offset:         184
        .size:           4
        .value_kind:     hidden_block_count_z
      - .offset:         188
        .size:           2
        .value_kind:     hidden_group_size_x
      - .offset:         190
        .size:           2
        .value_kind:     hidden_group_size_y
      - .offset:         192
        .size:           2
        .value_kind:     hidden_group_size_z
      - .offset:         194
        .size:           2
        .value_kind:     hidden_remainder_x
      - .offset:         196
        .size:           2
        .value_kind:     hidden_remainder_y
      - .offset:         198
        .size:           2
        .value_kind:     hidden_remainder_z
      - .offset:         216
        .size:           8
        .value_kind:     hidden_global_offset_x
      - .offset:         224
        .size:           8
        .value_kind:     hidden_global_offset_y
      - .offset:         232
        .size:           8
        .value_kind:     hidden_global_offset_z
      - .offset:         240
        .size:           2
        .value_kind:     hidden_grid_dims
      - .offset:         264
        .size:           8
        .value_kind:     hidden_multigrid_sync_arg
      - .offset:         296
        .size:           4
        .value_kind:     hidden_dynamic_lds_size
    .group_segment_fixed_size: 0
    .kernarg_segment_align: 8
    .kernarg_segment_size: 432
    .language:       OpenCL C
    .language_version:
      - 2
      - 0
    .max_flat_workgroup_size: 512
    .name:           _Z6mk_fwd4Args
    .private_segment_fixed_size: 0
    .sgpr_count:     108
    .sgpr_spill_count: 189
    .symbol:         _Z6mk_fwd4Args.kd
    .uniform_work_group_size: 1
    .uses_dynamic_stack: false
    .vgpr_count:     256
    .vgpr_spill_count: 0
    .wavefront_size: 64
